# scan wave f32 MFMA; kk/r fragment registers shifted by 2 so pk_fma src0/src1 pairs sit in different VGPR banks
# speedup vs baseline: 1.0027x; 1.0027x over previous
.LBB0_565:
	s_lshl_b32 s0, s22, 2
	v_readlane_b32 s18, v253, 37
	s_add_i32 s3, s20, s0
	v_readlane_b32 s19, v253, 38
	s_and_b64 s[0:1], s[18:19], exec
	s_cselect_b32 s0, s3, s21
	s_or_b32 s1, s0, s86
	s_ashr_i32 s3, s0, 6
	s_bfe_u32 s15, s1, 0x50001
	s_lshl_b32 s1, s3, 10
	s_addk_i32 s1, 0x2000
	s_lshl_b32 s3, s3, 8
	s_and_b64 s[18:19], s[18:19], exec
	v_readlane_b32 s18, v253, 10
	v_readlane_b32 s19, v253, 11
	s_cselect_b32 s14, s3, s1
	s_mov_b64 s[36:37], -1
	s_and_b64 vcc, exec, s[18:19]
	s_cbranch_vccz .LBB0_578
	s_setprio 0
	s_andn2_b32 s0, s0, 63
	v_readlane_b32 s1, v253, 12
	s_or_b32 s0, s0, s1
	s_or_b32 s0, s15, s0
	s_ashr_i32 s1, s0, 31
	s_lshl_b64 s[36:37], s[0:1], 14
	v_readlane_b32 s18, v253, 0
	v_readlane_b32 s19, v253, 1
	s_load_dwordx2 s[42:43], s[18:19], 0x20
	s_load_dwordx2 s[40:41], s[18:19], 0x100
	v_mbcnt_lo_u32_b32 v217, -1, 0
	v_mbcnt_hi_u32_b32 v217, -1, v217
	v_and_b32_e32 v218, 31, v217
	v_lshrrev_b32_e32 v219, 5, v217
	v_lshlrev_b32_e32 v182, 1, v217
	v_lshlrev_b32_e32 v216, 8, v218
	v_lshl_add_u32 v216, v219, 4, v216
	v_lshlrev_b32_e32 v213, 4, v219
	v_lshlrev_b32_e32 v214, 11, v219
	v_lshl_add_u32 v214, v218, 2, v214
	v_add_u32_e32 v214, 0x1000, v214
	v_lshlrev_b32_e32 v215, 2, v217
	v_add_u32_e32 v215, 0x2800, v215
	s_and_b64 s[0:1], s[12:13], exec
	s_movk_i32 s39, 0x100
	s_movk_i32 s74, 0x1000
	s_cselect_b32 s39, s39, 0xffffff00
	s_cselect_b32 s74, s74, 0xfffff000
	s_cselect_b32 s3, 0, -1
	s_waitcnt lgkmcnt(0)
	s_lshl_b32 s0, s88, 12
	s_lshl_b32 s1, s15, 7
	s_add_i32 s0, s0, s1
	s_add_u32 s100, s40, s0
	s_addc_u32 s101, s41, 0
	s_add_u32 s98, s40, 0x9200000
	s_addc_u32 s99, s41, 0
	s_add_u32 s98, s98, s36
	s_addc_u32 s99, s99, s37
	v_readlane_b32 s0, v253, 35
	v_readlane_b32 s1, v253, 36
	s_and_b64 vcc, exec, s[0:1]
	s_cbranch_vccz .Lscan_zero_state
	s_add_u32 s0, s42, s36
	s_addc_u32 s1, s43, s37
	s_add_u32 s18, s0, 0x2000
	s_addc_u32 s19, s1, 0
	global_load_dwordx4 v[32:35], v216, s[0:1]
	global_load_dwordx4 v[36:39], v216, s[0:1] offset:32
	global_load_dwordx4 v[40:43], v216, s[0:1] offset:64
	global_load_dwordx4 v[44:47], v216, s[0:1] offset:96
	global_load_dwordx4 v[48:51], v216, s[0:1] offset:128
	global_load_dwordx4 v[52:55], v216, s[0:1] offset:160
	global_load_dwordx4 v[56:59], v216, s[0:1] offset:192
	global_load_dwordx4 v[60:63], v216, s[0:1] offset:224
	global_load_dwordx4 v[64:67], v216, s[18:19]
	global_load_dwordx4 v[68:71], v216, s[18:19] offset:32
	global_load_dwordx4 v[72:75], v216, s[18:19] offset:64
	global_load_dwordx4 v[76:79], v216, s[18:19] offset:96
	global_load_dwordx4 v[80:83], v216, s[18:19] offset:128
	global_load_dwordx4 v[84:87], v216, s[18:19] offset:160
	global_load_dwordx4 v[88:91], v216, s[18:19] offset:192
	global_load_dwordx4 v[92:95], v216, s[18:19] offset:224
	s_waitcnt vmcnt(0)
	s_branch .Lscan_state_ready

.Lscan_chunk:
	s_add_i32 s0, s38, -1
	s_and_b32 s1, s0, 1
	s_lshl_b32 s1, s1, 2
	s_or_b32 s1, s1, s86
	s_mulk_i32 s1, 0x3000
	s_add_i32 s1, s1, 16
	s_add_i32 s17, s1, s59
	v_add_u32_e32 v183, s1, v213
	v_add_u32_e32 v179, s17, v213
	v_add_u32_e32 v180, s17, v214
	v_add_u32_e32 v181, s17, v215
	ds_read_b128 v[98:101], v179 offset:2048
	ds_read_b128 v[102:105], v179 offset:2080
	ds_read_b128 v[106:109], v179 offset:2112
	ds_read_b128 v[110:113], v179 offset:2144
	ds_read_b128 v[114:117], v179 offset:2176
	ds_read_b128 v[118:121], v179 offset:2208
	ds_read_b128 v[122:125], v179 offset:2240
	ds_read_b128 v[126:129], v179 offset:2272
	ds_read_b32 v170, v180
	ds_read_b32 v171, v180 offset:128
	ds_read_b32 v174, v181
	s_lshl_b32 s0, s0, 3
	s_sub_i32 s1, s61, s0
	s_and_b64 s[18:19], s[12:13], exec
	s_cselect_b32 s0, s0, s1
	s_add_i32 s0, s0, s14
	s_lshr_b32 s1, s59, 8
	s_add_i32 s0, s0, s1
	s_lshl_b32 s0, s0, 12
	s_add_u32 s42, s100, s0
	s_addc_u32 s43, s101, 0
	s_waitcnt lgkmcnt(0)
	v_pk_mul_f32 v[162:163], v[32:33], v[98:99]
	v_pk_mul_f32 v[166:167], v[64:65], v[98:99]
	v_pk_fma_f32 v[162:163], v[34:35], v[100:101], v[162:163]
	v_pk_fma_f32 v[166:167], v[66:67], v[100:101], v[166:167]
	v_pk_fma_f32 v[162:163], v[36:37], v[102:103], v[162:163]
	v_pk_fma_f32 v[166:167], v[68:69], v[102:103], v[166:167]
	v_pk_fma_f32 v[162:163], v[38:39], v[104:105], v[162:163]
	v_pk_fma_f32 v[166:167], v[70:71], v[104:105], v[166:167]
	v_pk_fma_f32 v[162:163], v[40:41], v[106:107], v[162:163]
	v_pk_fma_f32 v[166:167], v[72:73], v[106:107], v[166:167]
	v_pk_fma_f32 v[162:163], v[42:43], v[108:109], v[162:163]
	v_pk_fma_f32 v[166:167], v[74:75], v[108:109], v[166:167]
	v_pk_fma_f32 v[162:163], v[44:45], v[110:111], v[162:163]
	v_pk_fma_f32 v[166:167], v[76:77], v[110:111], v[166:167]
	v_pk_fma_f32 v[162:163], v[46:47], v[112:113], v[162:163]
	v_pk_fma_f32 v[166:167], v[78:79], v[112:113], v[166:167]
	v_pk_fma_f32 v[162:163], v[48:49], v[114:115], v[162:163]
	v_pk_fma_f32 v[166:167], v[80:81], v[114:115], v[166:167]
	v_pk_fma_f32 v[162:163], v[50:51], v[116:117], v[162:163]
	v_pk_fma_f32 v[166:167], v[82:83], v[116:117], v[166:167]
	v_pk_fma_f32 v[162:163], v[52:53], v[118:119], v[162:163]
	v_pk_fma_f32 v[166:167], v[84:85], v[118:119], v[166:167]
	v_pk_fma_f32 v[162:163], v[54:55], v[120:121], v[162:163]
	v_pk_fma_f32 v[166:167], v[86:87], v[120:121], v[166:167]
	v_pk_fma_f32 v[162:163], v[56:57], v[122:123], v[162:163]
	v_pk_fma_f32 v[166:167], v[88:89], v[122:123], v[166:167]
	v_pk_fma_f32 v[162:163], v[58:59], v[124:125], v[162:163]
	v_pk_fma_f32 v[166:167], v[90:91], v[124:125], v[166:167]
	v_pk_fma_f32 v[162:163], v[60:61], v[126:127], v[162:163]
	v_pk_fma_f32 v[166:167], v[92:93], v[126:127], v[166:167]
	v_pk_fma_f32 v[162:163], v[62:63], v[128:129], v[162:163]
	v_pk_fma_f32 v[166:167], v[94:95], v[128:129], v[166:167]
	v_add_f32_e32 v162, v162, v163
	v_add_f32_e32 v166, v166, v167
	s_nop 1
	v_permlane32_swap_b32_e32 v162, v166
	v_add_f32_e64 v176, -v162, -v166
	s_nop 1
	v_permlane32_swap_b32_e32 v176, v174
	s_nop 1
	v_mfma_f32_32x32x2_f32 v[32:47], v170, v176, v[32:47]
	ds_read_b128 v[130:133], v179 offset:8192
	ds_read_b128 v[134:137], v179 offset:8224
	ds_read_b128 v[138:141], v179 offset:8256
	ds_read_b128 v[142:145], v179 offset:8288
	ds_read_b128 v[146:149], v179 offset:8320
	ds_read_b128 v[150:153], v179 offset:8352
	ds_read_b128 v[154:157], v179 offset:8384
	ds_read_b128 v[158:161], v179 offset:8416
	v_mfma_f32_32x32x2_f32 v[48:63], v171, v176, v[48:63]
	v_add_u32_e32 v179, s39, v179
	v_add_u32_e32 v180, s39, v180
	v_add_u32_e32 v181, s39, v181
	ds_read_b128 v[98:101], v179 offset:2048
	ds_read_b128 v[102:105], v179 offset:2080
	ds_read_b128 v[106:109], v179 offset:2112
	ds_read_b128 v[110:113], v179 offset:2144
	ds_read_b128 v[114:117], v179 offset:2176
	ds_read_b128 v[118:121], v179 offset:2208
	ds_read_b128 v[122:125], v179 offset:2240
	ds_read_b128 v[126:129], v179 offset:2272
	v_mfma_f32_32x32x2_f32 v[64:79], v170, v174, v[64:79]
	ds_read_b32 v172, v180
	ds_read_b32 v173, v180 offset:128
	ds_read_b32 v175, v181
	v_mfma_f32_32x32x2_f32 v[80:95], v171, v174, v[80:95]
	s_nop 7
	s_nop 7
	s_nop 3
	s_waitcnt lgkmcnt(0)
	v_pk_mul_f32 v[162:163], v[32:33], v[98:99]
	v_pk_mul_f32 v[164:165], v[32:33], v[130:131]
	v_pk_mul_f32 v[166:167], v[64:65], v[98:99]
	v_pk_mul_f32 v[168:169], v[64:65], v[130:131]
	v_pk_fma_f32 v[162:163], v[34:35], v[100:101], v[162:163]
	v_pk_fma_f32 v[164:165], v[34:35], v[132:133], v[164:165]
	v_pk_fma_f32 v[166:167], v[66:67], v[100:101], v[166:167]
	v_pk_fma_f32 v[168:169], v[66:67], v[132:133], v[168:169]
	v_pk_fma_f32 v[162:163], v[36:37], v[102:103], v[162:163]
	v_pk_fma_f32 v[164:165], v[36:37], v[134:135], v[164:165]
	v_pk_fma_f32 v[166:167], v[68:69], v[102:103], v[166:167]
	v_pk_fma_f32 v[168:169], v[68:69], v[134:135], v[168:169]
	v_pk_fma_f32 v[162:163], v[38:39], v[104:105], v[162:163]
	v_pk_fma_f32 v[164:165], v[38:39], v[136:137], v[164:165]
	v_pk_fma_f32 v[166:167], v[70:71], v[104:105], v[166:167]
	v_pk_fma_f32 v[168:169], v[70:71], v[136:137], v[168:169]
	v_pk_fma_f32 v[162:163], v[40:41], v[106:107], v[162:163]
	v_pk_fma_f32 v[164:165], v[40:41], v[138:139], v[164:165]
	v_pk_fma_f32 v[166:167], v[72:73], v[106:107], v[166:167]
	v_pk_fma_f32 v[168:169], v[72:73], v[138:139], v[168:169]
	v_pk_fma_f32 v[162:163], v[42:43], v[108:109], v[162:163]
	v_pk_fma_f32 v[164:165], v[42:43], v[140:141], v[164:165]
	v_pk_fma_f32 v[166:167], v[74:75], v[108:109], v[166:167]
	v_pk_fma_f32 v[168:169], v[74:75], v[140:141], v[168:169]
	v_pk_fma_f32 v[162:163], v[44:45], v[110:111], v[162:163]
	v_pk_fma_f32 v[164:165], v[44:45], v[142:143], v[164:165]
	v_pk_fma_f32 v[166:167], v[76:77], v[110:111], v[166:167]
	v_pk_fma_f32 v[168:169], v[76:77], v[142:143], v[168:169]
	v_pk_fma_f32 v[162:163], v[46:47], v[112:113], v[162:163]
	v_pk_fma_f32 v[164:165], v[46:47], v[144:145], v[164:165]
	v_pk_fma_f32 v[166:167], v[78:79], v[112:113], v[166:167]
	v_pk_fma_f32 v[168:169], v[78:79], v[144:145], v[168:169]
	v_pk_fma_f32 v[162:163], v[48:49], v[114:115], v[162:163]
	v_pk_fma_f32 v[164:165], v[48:49], v[146:147], v[164:165]
	v_pk_fma_f32 v[166:167], v[80:81], v[114:115], v[166:167]
	v_pk_fma_f32 v[168:169], v[80:81], v[146:147], v[168:169]
	v_pk_fma_f32 v[162:163], v[50:51], v[116:117], v[162:163]
	v_pk_fma_f32 v[164:165], v[50:51], v[148:149], v[164:165]
	v_pk_fma_f32 v[166:167], v[82:83], v[116:117], v[166:167]
	v_pk_fma_f32 v[168:169], v[82:83], v[148:149], v[168:169]
	v_pk_fma_f32 v[162:163], v[52:53], v[118:119], v[162:163]
	v_pk_fma_f32 v[164:165], v[52:53], v[150:151], v[164:165]
	v_pk_fma_f32 v[166:167], v[84:85], v[118:119], v[166:167]
	v_pk_fma_f32 v[168:169], v[84:85], v[150:151], v[168:169]
	v_pk_fma_f32 v[162:163], v[54:55], v[120:121], v[162:163]
	v_pk_fma_f32 v[164:165], v[54:55], v[152:153], v[164:165]
	v_pk_fma_f32 v[166:167], v[86:87], v[120:121], v[166:167]
	v_pk_fma_f32 v[168:169], v[86:87], v[152:153], v[168:169]
	v_pk_fma_f32 v[162:163], v[56:57], v[122:123], v[162:163]
	v_pk_fma_f32 v[164:165], v[56:57], v[154:155], v[164:165]
	v_pk_fma_f32 v[166:167], v[88:89], v[122:123], v[166:167]
	v_pk_fma_f32 v[168:169], v[88:89], v[154:155], v[168:169]
	v_pk_fma_f32 v[162:163], v[58:59], v[124:125], v[162:163]
	v_pk_fma_f32 v[164:165], v[58:59], v[156:157], v[164:165]
	v_pk_fma_f32 v[166:167], v[90:91], v[124:125], v[166:167]
	v_pk_fma_f32 v[168:169], v[90:91], v[156:157], v[168:169]
	v_pk_fma_f32 v[162:163], v[60:61], v[126:127], v[162:163]
	v_pk_fma_f32 v[164:165], v[60:61], v[158:159], v[164:165]
	v_pk_fma_f32 v[166:167], v[92:93], v[126:127], v[166:167]
	v_pk_fma_f32 v[168:169], v[92:93], v[158:159], v[168:169]
	v_pk_fma_f32 v[162:163], v[62:63], v[128:129], v[162:163]
	v_pk_fma_f32 v[164:165], v[62:63], v[160:161], v[164:165]
	v_pk_fma_f32 v[166:167], v[94:95], v[128:129], v[166:167]
	v_pk_fma_f32 v[168:169], v[94:95], v[160:161], v[168:169]
	v_add_f32_e32 v162, v162, v163
	v_add_f32_e32 v166, v166, v167
	v_add_f32_e32 v164, v164, v165
	v_add_f32_e32 v168, v168, v169
	v_permlane32_swap_b32_e32 v162, v166
	v_add_f32_e64 v176, -v162, -v166
	v_permlane32_swap_b32_e32 v164, v168
	v_add_f32_e32 v177, v164, v168
	v_permlane32_swap_b32_e32 v176, v175
	v_cvt_pk_bf16_f32 v178, v177, v177
	s_nop 0
	v_mfma_f32_32x32x2_f32 v[32:47], v172, v176, v[32:47]
	ds_read_b128 v[130:133], v179 offset:8192
	ds_read_b128 v[134:137], v179 offset:8224
	ds_read_b128 v[138:141], v179 offset:8256
	ds_read_b128 v[142:145], v179 offset:8288
	ds_read_b128 v[146:149], v179 offset:8320
	ds_read_b128 v[150:153], v179 offset:8352
	ds_read_b128 v[154:157], v179 offset:8384
	ds_read_b128 v[158:161], v179 offset:8416
	v_mfma_f32_32x32x2_f32 v[48:63], v173, v176, v[48:63]
	v_add_u32_e32 v179, s39, v179
	v_add_u32_e32 v180, s39, v180
	v_add_u32_e32 v181, s39, v181
	ds_read_b128 v[98:101], v179 offset:2048
	ds_read_b128 v[102:105], v179 offset:2080
	ds_read_b128 v[106:109], v179 offset:2112
	ds_read_b128 v[110:113], v179 offset:2144
	ds_read_b128 v[114:117], v179 offset:2176
	ds_read_b128 v[118:121], v179 offset:2208
	ds_read_b128 v[122:125], v179 offset:2240
	ds_read_b128 v[126:129], v179 offset:2272
	v_mfma_f32_32x32x2_f32 v[64:79], v172, v175, v[64:79]
	ds_read_b32 v170, v180
	ds_read_b32 v171, v180 offset:128
	ds_read_b32 v174, v181
	v_mfma_f32_32x32x2_f32 v[80:95], v173, v175, v[80:95]
	global_store_short v182, v178, s[42:43]
	s_add_u32 s42, s42, s74
	s_addc_u32 s43, s43, s3
	s_nop 7
	s_nop 7
	s_nop 3
	s_waitcnt lgkmcnt(0)
	v_pk_mul_f32 v[162:163], v[32:33], v[98:99]
	v_pk_mul_f32 v[164:165], v[32:33], v[130:131]
	v_pk_mul_f32 v[166:167], v[64:65], v[98:99]
	v_pk_mul_f32 v[168:169], v[64:65], v[130:131]
	v_pk_fma_f32 v[162:163], v[34:35], v[100:101], v[162:163]
	v_pk_fma_f32 v[164:165], v[34:35], v[132:133], v[164:165]
	v_pk_fma_f32 v[166:167], v[66:67], v[100:101], v[166:167]
	v_pk_fma_f32 v[168:169], v[66:67], v[132:133], v[168:169]
	v_pk_fma_f32 v[162:163], v[36:37], v[102:103], v[162:163]
	v_pk_fma_f32 v[164:165], v[36:37], v[134:135], v[164:165]
	v_pk_fma_f32 v[166:167], v[68:69], v[102:103], v[166:167]
	v_pk_fma_f32 v[168:169], v[68:69], v[134:135], v[168:169]
	v_pk_fma_f32 v[162:163], v[38:39], v[104:105], v[162:163]
	v_pk_fma_f32 v[164:165], v[38:39], v[136:137], v[164:165]
	v_pk_fma_f32 v[166:167], v[70:71], v[104:105], v[166:167]
	v_pk_fma_f32 v[168:169], v[70:71], v[136:137], v[168:169]
	v_pk_fma_f32 v[162:163], v[40:41], v[106:107], v[162:163]
	v_pk_fma_f32 v[164:165], v[40:41], v[138:139], v[164:165]
	v_pk_fma_f32 v[166:167], v[72:73], v[106:107], v[166:167]
	v_pk_fma_f32 v[168:169], v[72:73], v[138:139], v[168:169]
	v_pk_fma_f32 v[162:163], v[42:43], v[108:109], v[162:163]
	v_pk_fma_f32 v[164:165], v[42:43], v[140:141], v[164:165]
	v_pk_fma_f32 v[166:167], v[74:75], v[108:109], v[166:167]
	v_pk_fma_f32 v[168:169], v[74:75], v[140:141], v[168:169]
	v_pk_fma_f32 v[162:163], v[44:45], v[110:111], v[162:163]
	v_pk_fma_f32 v[164:165], v[44:45], v[142:143], v[164:165]
	v_pk_fma_f32 v[166:167], v[76:77], v[110:111], v[166:167]
	v_pk_fma_f32 v[168:169], v[76:77], v[142:143], v[168:169]
	v_pk_fma_f32 v[162:163], v[46:47], v[112:113], v[162:163]
	v_pk_fma_f32 v[164:165], v[46:47], v[144:145], v[164:165]
	v_pk_fma_f32 v[166:167], v[78:79], v[112:113], v[166:167]
	v_pk_fma_f32 v[168:169], v[78:79], v[144:145], v[168:169]
	v_pk_fma_f32 v[162:163], v[48:49], v[114:115], v[162:163]
	v_pk_fma_f32 v[164:165], v[48:49], v[146:147], v[164:165]
	v_pk_fma_f32 v[166:167], v[80:81], v[114:115], v[166:167]
	v_pk_fma_f32 v[168:169], v[80:81], v[146:147], v[168:169]
	v_pk_fma_f32 v[162:163], v[50:51], v[116:117], v[162:163]
	v_pk_fma_f32 v[164:165], v[50:51], v[148:149], v[164:165]
	v_pk_fma_f32 v[166:167], v[82:83], v[116:117], v[166:167]
	v_pk_fma_f32 v[168:169], v[82:83], v[148:149], v[168:169]
	v_pk_fma_f32 v[162:163], v[52:53], v[118:119], v[162:163]
	v_pk_fma_f32 v[164:165], v[52:53], v[150:151], v[164:165]
	v_pk_fma_f32 v[166:167], v[84:85], v[118:119], v[166:167]
	v_pk_fma_f32 v[168:169], v[84:85], v[150:151], v[168:169]
	v_pk_fma_f32 v[162:163], v[54:55], v[120:121], v[162:163]
	v_pk_fma_f32 v[164:165], v[54:55], v[152:153], v[164:165]
	v_pk_fma_f32 v[166:167], v[86:87], v[120:121], v[166:167]
	v_pk_fma_f32 v[168:169], v[86:87], v[152:153], v[168:169]
	v_pk_fma_f32 v[162:163], v[56:57], v[122:123], v[162:163]
	v_pk_fma_f32 v[164:165], v[56:57], v[154:155], v[164:165]
	v_pk_fma_f32 v[166:167], v[88:89], v[122:123], v[166:167]
	v_pk_fma_f32 v[168:169], v[88:89], v[154:155], v[168:169]
	v_pk_fma_f32 v[162:163], v[58:59], v[124:125], v[162:163]
	v_pk_fma_f32 v[164:165], v[58:59], v[156:157], v[164:165]
	v_pk_fma_f32 v[166:167], v[90:91], v[124:125], v[166:167]
	v_pk_fma_f32 v[168:169], v[90:91], v[156:157], v[168:169]
	v_pk_fma_f32 v[162:163], v[60:61], v[126:127], v[162:163]
	v_pk_fma_f32 v[164:165], v[60:61], v[158:159], v[164:165]
	v_pk_fma_f32 v[166:167], v[92:93], v[126:127], v[166:167]
	v_pk_fma_f32 v[168:169], v[92:93], v[158:159], v[168:169]
	v_pk_fma_f32 v[162:163], v[62:63], v[128:129], v[162:163]
	v_pk_fma_f32 v[164:165], v[62:63], v[160:161], v[164:165]
	v_pk_fma_f32 v[166:167], v[94:95], v[128:129], v[166:167]
	v_pk_fma_f32 v[168:169], v[94:95], v[160:161], v[168:169]
	v_add_f32_e32 v162, v162, v163
	v_add_f32_e32 v166, v166, v167
	v_add_f32_e32 v164, v164, v165
	v_add_f32_e32 v168, v168, v169
	v_permlane32_swap_b32_e32 v162, v166
	v_add_f32_e64 v176, -v162, -v166
	v_permlane32_swap_b32_e32 v164, v168
	v_add_f32_e32 v177, v164, v168
	v_permlane32_swap_b32_e32 v176, v174
	v_cvt_pk_bf16_f32 v178, v177, v177
	s_nop 0
	v_mfma_f32_32x32x2_f32 v[32:47], v170, v176, v[32:47]
	ds_read_b128 v[130:133], v179 offset:8192
	ds_read_b128 v[134:137], v179 offset:8224
	ds_read_b128 v[138:141], v179 offset:8256
	ds_read_b128 v[142:145], v179 offset:8288
	ds_read_b128 v[146:149], v179 offset:8320
	ds_read_b128 v[150:153], v179 offset:8352
	ds_read_b128 v[154:157], v179 offset:8384
	ds_read_b128 v[158:161], v179 offset:8416
	v_mfma_f32_32x32x2_f32 v[48:63], v171, v176, v[48:63]
	v_add_u32_e32 v179, s39, v179
	v_add_u32_e32 v180, s39, v180
	v_add_u32_e32 v181, s39, v181
	ds_read_b128 v[98:101], v179 offset:2048
	ds_read_b128 v[102:105], v179 offset:2080
	ds_read_b128 v[106:109], v179 offset:2112
	ds_read_b128 v[110:113], v179 offset:2144
	ds_read_b128 v[114:117], v179 offset:2176
	ds_read_b128 v[118:121], v179 offset:2208
	ds_read_b128 v[122:125], v179 offset:2240
	ds_read_b128 v[126:129], v179 offset:2272
	v_mfma_f32_32x32x2_f32 v[64:79], v170, v174, v[64:79]
	ds_read_b32 v172, v180
	ds_read_b32 v173, v180 offset:128
	ds_read_b32 v175, v181
	v_mfma_f32_32x32x2_f32 v[80:95], v171, v174, v[80:95]
	global_store_short v182, v178, s[42:43]
	s_add_u32 s42, s42, s74
	s_addc_u32 s43, s43, s3
	s_nop 7
	s_nop 7
	s_nop 3
	s_waitcnt lgkmcnt(0)
	v_pk_mul_f32 v[162:163], v[32:33], v[98:99]
	v_pk_mul_f32 v[164:165], v[32:33], v[130:131]
	v_pk_mul_f32 v[166:167], v[64:65], v[98:99]
	v_pk_mul_f32 v[168:169], v[64:65], v[130:131]
	v_pk_fma_f32 v[162:163], v[34:35], v[100:101], v[162:163]
	v_pk_fma_f32 v[164:165], v[34:35], v[132:133], v[164:165]
	v_pk_fma_f32 v[166:167], v[66:67], v[100:101], v[166:167]
	v_pk_fma_f32 v[168:169], v[66:67], v[132:133], v[168:169]
	v_pk_fma_f32 v[162:163], v[36:37], v[102:103], v[162:163]
	v_pk_fma_f32 v[164:165], v[36:37], v[134:135], v[164:165]
	v_pk_fma_f32 v[166:167], v[68:69], v[102:103], v[166:167]
	v_pk_fma_f32 v[168:169], v[68:69], v[134:135], v[168:169]
	v_pk_fma_f32 v[162:163], v[38:39], v[104:105], v[162:163]
	v_pk_fma_f32 v[164:165], v[38:39], v[136:137], v[164:165]
	v_pk_fma_f32 v[166:167], v[70:71], v[104:105], v[166:167]
	v_pk_fma_f32 v[168:169], v[70:71], v[136:137], v[168:169]
	v_pk_fma_f32 v[162:163], v[40:41], v[106:107], v[162:163]
	v_pk_fma_f32 v[164:165], v[40:41], v[138:139], v[164:165]
	v_pk_fma_f32 v[166:167], v[72:73], v[106:107], v[166:167]
	v_pk_fma_f32 v[168:169], v[72:73], v[138:139], v[168:169]
	v_pk_fma_f32 v[162:163], v[42:43], v[108:109], v[162:163]
	v_pk_fma_f32 v[164:165], v[42:43], v[140:141], v[164:165]
	v_pk_fma_f32 v[166:167], v[74:75], v[108:109], v[166:167]
	v_pk_fma_f32 v[168:169], v[74:75], v[140:141], v[168:169]
	v_pk_fma_f32 v[162:163], v[44:45], v[110:111], v[162:163]
	v_pk_fma_f32 v[164:165], v[44:45], v[142:143], v[164:165]
	v_pk_fma_f32 v[166:167], v[76:77], v[110:111], v[166:167]
	v_pk_fma_f32 v[168:169], v[76:77], v[142:143], v[168:169]
	v_pk_fma_f32 v[162:163], v[46:47], v[112:113], v[162:163]
	v_pk_fma_f32 v[164:165], v[46:47], v[144:145], v[164:165]
	v_pk_fma_f32 v[166:167], v[78:79], v[112:113], v[166:167]
	v_pk_fma_f32 v[168:169], v[78:79], v[144:145], v[168:169]
	v_pk_fma_f32 v[162:163], v[48:49], v[114:115], v[162:163]
	v_pk_fma_f32 v[164:165], v[48:49], v[146:147], v[164:165]
	v_pk_fma_f32 v[166:167], v[80:81], v[114:115], v[166:167]
	v_pk_fma_f32 v[168:169], v[80:81], v[146:147], v[168:169]
	v_pk_fma_f32 v[162:163], v[50:51], v[116:117], v[162:163]
	v_pk_fma_f32 v[164:165], v[50:51], v[148:149], v[164:165]
	v_pk_fma_f32 v[166:167], v[82:83], v[116:117], v[166:167]
	v_pk_fma_f32 v[168:169], v[82:83], v[148:149], v[168:169]
	v_pk_fma_f32 v[162:163], v[52:53], v[118:119], v[162:163]
	v_pk_fma_f32 v[164:165], v[52:53], v[150:151], v[164:165]
	v_pk_fma_f32 v[166:167], v[84:85], v[118:119], v[166:167]
	v_pk_fma_f32 v[168:169], v[84:85], v[150:151], v[168:169]
	v_pk_fma_f32 v[162:163], v[54:55], v[120:121], v[162:163]
	v_pk_fma_f32 v[164:165], v[54:55], v[152:153], v[164:165]
	v_pk_fma_f32 v[166:167], v[86:87], v[120:121], v[166:167]
	v_pk_fma_f32 v[168:169], v[86:87], v[152:153], v[168:169]
	v_pk_fma_f32 v[162:163], v[56:57], v[122:123], v[162:163]
	v_pk_fma_f32 v[164:165], v[56:57], v[154:155], v[164:165]
	v_pk_fma_f32 v[166:167], v[88:89], v[122:123], v[166:167]
	v_pk_fma_f32 v[168:169], v[88:89], v[154:155], v[168:169]
	v_pk_fma_f32 v[162:163], v[58:59], v[124:125], v[162:163]
	v_pk_fma_f32 v[164:165], v[58:59], v[156:157], v[164:165]
	v_pk_fma_f32 v[166:167], v[90:91], v[124:125], v[166:167]
	v_pk_fma_f32 v[168:169], v[90:91], v[156:157], v[168:169]
	v_pk_fma_f32 v[162:163], v[60:61], v[126:127], v[162:163]
	v_pk_fma_f32 v[164:165], v[60:61], v[158:159], v[164:165]
	v_pk_fma_f32 v[166:167], v[92:93], v[126:127], v[166:167]
	v_pk_fma_f32 v[168:169], v[92:93], v[158:159], v[168:169]
	v_pk_fma_f32 v[162:163], v[62:63], v[128:129], v[162:163]
	v_pk_fma_f32 v[164:165], v[62:63], v[160:161], v[164:165]
	v_pk_fma_f32 v[166:167], v[94:95], v[128:129], v[166:167]
	v_pk_fma_f32 v[168:169], v[94:95], v[160:161], v[168:169]
	v_add_f32_e32 v162, v162, v163
	v_add_f32_e32 v166, v166, v167
	v_add_f32_e32 v164, v164, v165
	v_add_f32_e32 v168, v168, v169
	v_permlane32_swap_b32_e32 v162, v166
	v_add_f32_e64 v176, -v162, -v166
	v_permlane32_swap_b32_e32 v164, v168
	v_add_f32_e32 v177, v164, v168
	v_permlane32_swap_b32_e32 v176, v175
	v_cvt_pk_bf16_f32 v178, v177, v177
	s_nop 0
	v_mfma_f32_32x32x2_f32 v[32:47], v172, v176, v[32:47]
	ds_read_b128 v[130:133], v179 offset:8192
	ds_read_b128 v[134:137], v179 offset:8224
	ds_read_b128 v[138:141], v179 offset:8256
	ds_read_b128 v[142:145], v179 offset:8288
	ds_read_b128 v[146:149], v179 offset:8320
	ds_read_b128 v[150:153], v179 offset:8352
	ds_read_b128 v[154:157], v179 offset:8384
	ds_read_b128 v[158:161], v179 offset:8416
	v_mfma_f32_32x32x2_f32 v[48:63], v173, v176, v[48:63]
	v_add_u32_e32 v179, s39, v179
	v_add_u32_e32 v180, s39, v180
	v_add_u32_e32 v181, s39, v181
	ds_read_b128 v[98:101], v179 offset:2048
	ds_read_b128 v[102:105], v179 offset:2080
	ds_read_b128 v[106:109], v179 offset:2112
	ds_read_b128 v[110:113], v179 offset:2144
	ds_read_b128 v[114:117], v179 offset:2176
	ds_read_b128 v[118:121], v179 offset:2208
	ds_read_b128 v[122:125], v179 offset:2240
	ds_read_b128 v[126:129], v179 offset:2272
	v_mfma_f32_32x32x2_f32 v[64:79], v172, v175, v[64:79]
	ds_read_b32 v170, v180
	ds_read_b32 v171, v180 offset:128
	ds_read_b32 v174, v181
	v_mfma_f32_32x32x2_f32 v[80:95], v173, v175, v[80:95]
	global_store_short v182, v178, s[42:43]
	s_add_u32 s42, s42, s74
	s_addc_u32 s43, s43, s3
	s_nop 7
	s_nop 7
	s_nop 3
	s_waitcnt lgkmcnt(0)
	v_pk_mul_f32 v[162:163], v[32:33], v[98:99]
	v_pk_mul_f32 v[164:165], v[32:33], v[130:131]
	v_pk_mul_f32 v[166:167], v[64:65], v[98:99]
	v_pk_mul_f32 v[168:169], v[64:65], v[130:131]
	v_pk_fma_f32 v[162:163], v[34:35], v[100:101], v[162:163]
	v_pk_fma_f32 v[164:165], v[34:35], v[132:133], v[164:165]
	v_pk_fma_f32 v[166:167], v[66:67], v[100:101], v[166:167]
	v_pk_fma_f32 v[168:169], v[66:67], v[132:133], v[168:169]
	v_pk_fma_f32 v[162:163], v[36:37], v[102:103], v[162:163]
	v_pk_fma_f32 v[164:165], v[36:37], v[134:135], v[164:165]
	v_pk_fma_f32 v[166:167], v[68:69], v[102:103], v[166:167]
	v_pk_fma_f32 v[168:169], v[68:69], v[134:135], v[168:169]
	v_pk_fma_f32 v[162:163], v[38:39], v[104:105], v[162:163]
	v_pk_fma_f32 v[164:165], v[38:39], v[136:137], v[164:165]
	v_pk_fma_f32 v[166:167], v[70:71], v[104:105], v[166:167]
	v_pk_fma_f32 v[168:169], v[70:71], v[136:137], v[168:169]
	v_pk_fma_f32 v[162:163], v[40:41], v[106:107], v[162:163]
	v_pk_fma_f32 v[164:165], v[40:41], v[138:139], v[164:165]
	v_pk_fma_f32 v[166:167], v[72:73], v[106:107], v[166:167]
	v_pk_fma_f32 v[168:169], v[72:73], v[138:139], v[168:169]
	v_pk_fma_f32 v[162:163], v[42:43], v[108:109], v[162:163]
	v_pk_fma_f32 v[164:165], v[42:43], v[140:141], v[164:165]
	v_pk_fma_f32 v[166:167], v[74:75], v[108:109], v[166:167]
	v_pk_fma_f32 v[168:169], v[74:75], v[140:141], v[168:169]
	v_pk_fma_f32 v[162:163], v[44:45], v[110:111], v[162:163]
	v_pk_fma_f32 v[164:165], v[44:45], v[142:143], v[164:165]
	v_pk_fma_f32 v[166:167], v[76:77], v[110:111], v[166:167]
	v_pk_fma_f32 v[168:169], v[76:77], v[142:143], v[168:169]
	v_pk_fma_f32 v[162:163], v[46:47], v[112:113], v[162:163]
	v_pk_fma_f32 v[164:165], v[46:47], v[144:145], v[164:165]
	v_pk_fma_f32 v[166:167], v[78:79], v[112:113], v[166:167]
	v_pk_fma_f32 v[168:169], v[78:79], v[144:145], v[168:169]
	v_pk_fma_f32 v[162:163], v[48:49], v[114:115], v[162:163]
	v_pk_fma_f32 v[164:165], v[48:49], v[146:147], v[164:165]
	v_pk_fma_f32 v[166:167], v[80:81], v[114:115], v[166:167]
	v_pk_fma_f32 v[168:169], v[80:81], v[146:147], v[168:169]
	v_pk_fma_f32 v[162:163], v[50:51], v[116:117], v[162:163]
	v_pk_fma_f32 v[164:165], v[50:51], v[148:149], v[164:165]
	v_pk_fma_f32 v[166:167], v[82:83], v[116:117], v[166:167]
	v_pk_fma_f32 v[168:169], v[82:83], v[148:149], v[168:169]
	v_pk_fma_f32 v[162:163], v[52:53], v[118:119], v[162:163]
	v_pk_fma_f32 v[164:165], v[52:53], v[150:151], v[164:165]
	v_pk_fma_f32 v[166:167], v[84:85], v[118:119], v[166:167]
	v_pk_fma_f32 v[168:169], v[84:85], v[150:151], v[168:169]
	v_pk_fma_f32 v[162:163], v[54:55], v[120:121], v[162:163]
	v_pk_fma_f32 v[164:165], v[54:55], v[152:153], v[164:165]
	v_pk_fma_f32 v[166:167], v[86:87], v[120:121], v[166:167]
	v_pk_fma_f32 v[168:169], v[86:87], v[152:153], v[168:169]
	v_pk_fma_f32 v[162:163], v[56:57], v[122:123], v[162:163]
	v_pk_fma_f32 v[164:165], v[56:57], v[154:155], v[164:165]
	v_pk_fma_f32 v[166:167], v[88:89], v[122:123], v[166:167]
	v_pk_fma_f32 v[168:169], v[88:89], v[154:155], v[168:169]
	v_pk_fma_f32 v[162:163], v[58:59], v[124:125], v[162:163]
	v_pk_fma_f32 v[164:165], v[58:59], v[156:157], v[164:165]
	v_pk_fma_f32 v[166:167], v[90:91], v[124:125], v[166:167]
	v_pk_fma_f32 v[168:169], v[90:91], v[156:157], v[168:169]
	v_pk_fma_f32 v[162:163], v[60:61], v[126:127], v[162:163]
	v_pk_fma_f32 v[164:165], v[60:61], v[158:159], v[164:165]
	v_pk_fma_f32 v[166:167], v[92:93], v[126:127], v[166:167]
	v_pk_fma_f32 v[168:169], v[92:93], v[158:159], v[168:169]
	v_pk_fma_f32 v[162:163], v[62:63], v[128:129], v[162:163]
	v_pk_fma_f32 v[164:165], v[62:63], v[160:161], v[164:165]
	v_pk_fma_f32 v[166:167], v[94:95], v[128:129], v[166:167]
	v_pk_fma_f32 v[168:169], v[94:95], v[160:161], v[168:169]
	v_add_f32_e32 v162, v162, v163
	v_add_f32_e32 v166, v166, v167
	v_add_f32_e32 v164, v164, v165
	v_add_f32_e32 v168, v168, v169
	v_permlane32_swap_b32_e32 v162, v166
	v_add_f32_e64 v176, -v162, -v166
	v_permlane32_swap_b32_e32 v164, v168
	v_add_f32_e32 v177, v164, v168
	v_permlane32_swap_b32_e32 v176, v174
	v_cvt_pk_bf16_f32 v178, v177, v177
	s_nop 0
	v_mfma_f32_32x32x2_f32 v[32:47], v170, v176, v[32:47]
	ds_read_b128 v[130:133], v179 offset:8192
	ds_read_b128 v[134:137], v179 offset:8224
	ds_read_b128 v[138:141], v179 offset:8256
	ds_read_b128 v[142:145], v179 offset:8288
	ds_read_b128 v[146:149], v179 offset:8320
	ds_read_b128 v[150:153], v179 offset:8352
	ds_read_b128 v[154:157], v179 offset:8384
	ds_read_b128 v[158:161], v179 offset:8416
	v_mfma_f32_32x32x2_f32 v[48:63], v171, v176, v[48:63]
	v_add_u32_e32 v179, s39, v179
	v_add_u32_e32 v180, s39, v180
	v_add_u32_e32 v181, s39, v181
	ds_read_b128 v[98:101], v179 offset:2048
	ds_read_b128 v[102:105], v179 offset:2080
	ds_read_b128 v[106:109], v179 offset:2112
	ds_read_b128 v[110:113], v179 offset:2144
	ds_read_b128 v[114:117], v179 offset:2176
	ds_read_b128 v[118:121], v179 offset:2208
	ds_read_b128 v[122:125], v179 offset:2240
	ds_read_b128 v[126:129], v179 offset:2272
	v_mfma_f32_32x32x2_f32 v[64:79], v170, v174, v[64:79]
	ds_read_b32 v172, v180
	ds_read_b32 v173, v180 offset:128
	ds_read_b32 v175, v181
	v_mfma_f32_32x32x2_f32 v[80:95], v171, v174, v[80:95]
	global_store_short v182, v178, s[42:43]
	s_add_u32 s42, s42, s74
	s_addc_u32 s43, s43, s3
	s_nop 7
	s_nop 7
	s_nop 3
	s_waitcnt lgkmcnt(0)
	v_pk_mul_f32 v[162:163], v[32:33], v[98:99]
	v_pk_mul_f32 v[164:165], v[32:33], v[130:131]
	v_pk_mul_f32 v[166:167], v[64:65], v[98:99]
	v_pk_mul_f32 v[168:169], v[64:65], v[130:131]
	v_pk_fma_f32 v[162:163], v[34:35], v[100:101], v[162:163]
	v_pk_fma_f32 v[164:165], v[34:35], v[132:133], v[164:165]
	v_pk_fma_f32 v[166:167], v[66:67], v[100:101], v[166:167]
	v_pk_fma_f32 v[168:169], v[66:67], v[132:133], v[168:169]
	v_pk_fma_f32 v[162:163], v[36:37], v[102:103], v[162:163]
	v_pk_fma_f32 v[164:165], v[36:37], v[134:135], v[164:165]
	v_pk_fma_f32 v[166:167], v[68:69], v[102:103], v[166:167]
	v_pk_fma_f32 v[168:169], v[68:69], v[134:135], v[168:169]
	v_pk_fma_f32 v[162:163], v[38:39], v[104:105], v[162:163]
	v_pk_fma_f32 v[164:165], v[38:39], v[136:137], v[164:165]
	v_pk_fma_f32 v[166:167], v[70:71], v[104:105], v[166:167]
	v_pk_fma_f32 v[168:169], v[70:71], v[136:137], v[168:169]
	v_pk_fma_f32 v[162:163], v[40:41], v[106:107], v[162:163]
	v_pk_fma_f32 v[164:165], v[40:41], v[138:139], v[164:165]
	v_pk_fma_f32 v[166:167], v[72:73], v[106:107], v[166:167]
	v_pk_fma_f32 v[168:169], v[72:73], v[138:139], v[168:169]
	v_pk_fma_f32 v[162:163], v[42:43], v[108:109], v[162:163]
	v_pk_fma_f32 v[164:165], v[42:43], v[140:141], v[164:165]
	v_pk_fma_f32 v[166:167], v[74:75], v[108:109], v[166:167]
	v_pk_fma_f32 v[168:169], v[74:75], v[140:141], v[168:169]
	v_pk_fma_f32 v[162:163], v[44:45], v[110:111], v[162:163]
	v_pk_fma_f32 v[164:165], v[44:45], v[142:143], v[164:165]
	v_pk_fma_f32 v[166:167], v[76:77], v[110:111], v[166:167]
	v_pk_fma_f32 v[168:169], v[76:77], v[142:143], v[168:169]
	v_pk_fma_f32 v[162:163], v[46:47], v[112:113], v[162:163]
	v_pk_fma_f32 v[164:165], v[46:47], v[144:145], v[164:165]
	v_pk_fma_f32 v[166:167], v[78:79], v[112:113], v[166:167]
	v_pk_fma_f32 v[168:169], v[78:79], v[144:145], v[168:169]
	v_pk_fma_f32 v[162:163], v[48:49], v[114:115], v[162:163]
	v_pk_fma_f32 v[164:165], v[48:49], v[146:147], v[164:165]
	v_pk_fma_f32 v[166:167], v[80:81], v[114:115], v[166:167]
	v_pk_fma_f32 v[168:169], v[80:81], v[146:147], v[168:169]
	v_pk_fma_f32 v[162:163], v[50:51], v[116:117], v[162:163]
	v_pk_fma_f32 v[164:165], v[50:51], v[148:149], v[164:165]
	v_pk_fma_f32 v[166:167], v[82:83], v[116:117], v[166:167]
	v_pk_fma_f32 v[168:169], v[82:83], v[148:149], v[168:169]
	v_pk_fma_f32 v[162:163], v[52:53], v[118:119], v[162:163]
	v_pk_fma_f32 v[164:165], v[52:53], v[150:151], v[164:165]
	v_pk_fma_f32 v[166:167], v[84:85], v[118:119], v[166:167]
	v_pk_fma_f32 v[168:169], v[84:85], v[150:151], v[168:169]
	v_pk_fma_f32 v[162:163], v[54:55], v[120:121], v[162:163]
	v_pk_fma_f32 v[164:165], v[54:55], v[152:153], v[164:165]
	v_pk_fma_f32 v[166:167], v[86:87], v[120:121], v[166:167]
	v_pk_fma_f32 v[168:169], v[86:87], v[152:153], v[168:169]
	v_pk_fma_f32 v[162:163], v[56:57], v[122:123], v[162:163]
	v_pk_fma_f32 v[164:165], v[56:57], v[154:155], v[164:165]
	v_pk_fma_f32 v[166:167], v[88:89], v[122:123], v[166:167]
	v_pk_fma_f32 v[168:169], v[88:89], v[154:155], v[168:169]
	v_pk_fma_f32 v[162:163], v[58:59], v[124:125], v[162:163]
	v_pk_fma_f32 v[164:165], v[58:59], v[156:157], v[164:165]
	v_pk_fma_f32 v[166:167], v[90:91], v[124:125], v[166:167]
	v_pk_fma_f32 v[168:169], v[90:91], v[156:157], v[168:169]
	v_pk_fma_f32 v[162:163], v[60:61], v[126:127], v[162:163]
	v_pk_fma_f32 v[164:165], v[60:61], v[158:159], v[164:165]
	v_pk_fma_f32 v[166:167], v[92:93], v[126:127], v[166:167]
	v_pk_fma_f32 v[168:169], v[92:93], v[158:159], v[168:169]
	v_pk_fma_f32 v[162:163], v[62:63], v[128:129], v[162:163]
	v_pk_fma_f32 v[164:165], v[62:63], v[160:161], v[164:165]
	v_pk_fma_f32 v[166:167], v[94:95], v[128:129], v[166:167]
	v_pk_fma_f32 v[168:169], v[94:95], v[160:161], v[168:169]
	v_add_f32_e32 v162, v162, v163
	v_add_f32_e32 v166, v166, v167
	v_add_f32_e32 v164, v164, v165
	v_add_f32_e32 v168, v168, v169
	v_permlane32_swap_b32_e32 v162, v166
	v_add_f32_e64 v176, -v162, -v166
	v_permlane32_swap_b32_e32 v164, v168
	v_add_f32_e32 v177, v164, v168
	v_permlane32_swap_b32_e32 v176, v175
	v_cvt_pk_bf16_f32 v178, v177, v177
	s_nop 0
	v_mfma_f32_32x32x2_f32 v[32:47], v172, v176, v[32:47]
	ds_read_b128 v[130:133], v179 offset:8192
	ds_read_b128 v[134:137], v179 offset:8224
	ds_read_b128 v[138:141], v179 offset:8256
	ds_read_b128 v[142:145], v179 offset:8288
	ds_read_b128 v[146:149], v179 offset:8320
	ds_read_b128 v[150:153], v179 offset:8352
	ds_read_b128 v[154:157], v179 offset:8384
	ds_read_b128 v[158:161], v179 offset:8416
	v_mfma_f32_32x32x2_f32 v[48:63], v173, v176, v[48:63]
	v_add_u32_e32 v179, s39, v179
	v_add_u32_e32 v180, s39, v180
	v_add_u32_e32 v181, s39, v181
	ds_read_b128 v[98:101], v179 offset:2048
	ds_read_b128 v[102:105], v179 offset:2080
	ds_read_b128 v[106:109], v179 offset:2112
	ds_read_b128 v[110:113], v179 offset:2144
	ds_read_b128 v[114:117], v179 offset:2176
	ds_read_b128 v[118:121], v179 offset:2208
	ds_read_b128 v[122:125], v179 offset:2240
	ds_read_b128 v[126:129], v179 offset:2272
	v_mfma_f32_32x32x2_f32 v[64:79], v172, v175, v[64:79]
	ds_read_b32 v170, v180
	ds_read_b32 v171, v180 offset:128
	ds_read_b32 v174, v181
	v_mfma_f32_32x32x2_f32 v[80:95], v173, v175, v[80:95]
	global_store_short v182, v178, s[42:43]
	s_add_u32 s42, s42, s74
	s_addc_u32 s43, s43, s3
	s_nop 7
	s_nop 7
	s_nop 3
	s_waitcnt lgkmcnt(0)
	v_pk_mul_f32 v[162:163], v[32:33], v[98:99]
	v_pk_mul_f32 v[164:165], v[32:33], v[130:131]
	v_pk_mul_f32 v[166:167], v[64:65], v[98:99]
	v_pk_mul_f32 v[168:169], v[64:65], v[130:131]
	v_pk_fma_f32 v[162:163], v[34:35], v[100:101], v[162:163]
	v_pk_fma_f32 v[164:165], v[34:35], v[132:133], v[164:165]
	v_pk_fma_f32 v[166:167], v[66:67], v[100:101], v[166:167]
	v_pk_fma_f32 v[168:169], v[66:67], v[132:133], v[168:169]
	v_pk_fma_f32 v[162:163], v[36:37], v[102:103], v[162:163]
	v_pk_fma_f32 v[164:165], v[36:37], v[134:135], v[164:165]
	v_pk_fma_f32 v[166:167], v[68:69], v[102:103], v[166:167]
	v_pk_fma_f32 v[168:169], v[68:69], v[134:135], v[168:169]
	v_pk_fma_f32 v[162:163], v[38:39], v[104:105], v[162:163]
	v_pk_fma_f32 v[164:165], v[38:39], v[136:137], v[164:165]
	v_pk_fma_f32 v[166:167], v[70:71], v[104:105], v[166:167]
	v_pk_fma_f32 v[168:169], v[70:71], v[136:137], v[168:169]
	v_pk_fma_f32 v[162:163], v[40:41], v[106:107], v[162:163]
	v_pk_fma_f32 v[164:165], v[40:41], v[138:139], v[164:165]
	v_pk_fma_f32 v[166:167], v[72:73], v[106:107], v[166:167]
	v_pk_fma_f32 v[168:169], v[72:73], v[138:139], v[168:169]
	v_pk_fma_f32 v[162:163], v[42:43], v[108:109], v[162:163]
	v_pk_fma_f32 v[164:165], v[42:43], v[140:141], v[164:165]
	v_pk_fma_f32 v[166:167], v[74:75], v[108:109], v[166:167]
	v_pk_fma_f32 v[168:169], v[74:75], v[140:141], v[168:169]
	v_pk_fma_f32 v[162:163], v[44:45], v[110:111], v[162:163]
	v_pk_fma_f32 v[164:165], v[44:45], v[142:143], v[164:165]
	v_pk_fma_f32 v[166:167], v[76:77], v[110:111], v[166:167]
	v_pk_fma_f32 v[168:169], v[76:77], v[142:143], v[168:169]
	v_pk_fma_f32 v[162:163], v[46:47], v[112:113], v[162:163]
	v_pk_fma_f32 v[164:165], v[46:47], v[144:145], v[164:165]
	v_pk_fma_f32 v[166:167], v[78:79], v[112:113], v[166:167]
	v_pk_fma_f32 v[168:169], v[78:79], v[144:145], v[168:169]
	v_pk_fma_f32 v[162:163], v[48:49], v[114:115], v[162:163]
	v_pk_fma_f32 v[164:165], v[48:49], v[146:147], v[164:165]
	v_pk_fma_f32 v[166:167], v[80:81], v[114:115], v[166:167]
	v_pk_fma_f32 v[168:169], v[80:81], v[146:147], v[168:169]
	v_pk_fma_f32 v[162:163], v[50:51], v[116:117], v[162:163]
	v_pk_fma_f32 v[164:165], v[50:51], v[148:149], v[164:165]
	v_pk_fma_f32 v[166:167], v[82:83], v[116:117], v[166:167]
	v_pk_fma_f32 v[168:169], v[82:83], v[148:149], v[168:169]
	v_pk_fma_f32 v[162:163], v[52:53], v[118:119], v[162:163]
	v_pk_fma_f32 v[164:165], v[52:53], v[150:151], v[164:165]
	v_pk_fma_f32 v[166:167], v[84:85], v[118:119], v[166:167]
	v_pk_fma_f32 v[168:169], v[84:85], v[150:151], v[168:169]
	v_pk_fma_f32 v[162:163], v[54:55], v[120:121], v[162:163]
	v_pk_fma_f32 v[164:165], v[54:55], v[152:153], v[164:165]
	v_pk_fma_f32 v[166:167], v[86:87], v[120:121], v[166:167]
	v_pk_fma_f32 v[168:169], v[86:87], v[152:153], v[168:169]
	v_pk_fma_f32 v[162:163], v[56:57], v[122:123], v[162:163]
	v_pk_fma_f32 v[164:165], v[56:57], v[154:155], v[164:165]
	v_pk_fma_f32 v[166:167], v[88:89], v[122:123], v[166:167]
	v_pk_fma_f32 v[168:169], v[88:89], v[154:155], v[168:169]
	v_pk_fma_f32 v[162:163], v[58:59], v[124:125], v[162:163]
	v_pk_fma_f32 v[164:165], v[58:59], v[156:157], v[164:165]
	v_pk_fma_f32 v[166:167], v[90:91], v[124:125], v[166:167]
	v_pk_fma_f32 v[168:169], v[90:91], v[156:157], v[168:169]
	v_pk_fma_f32 v[162:163], v[60:61], v[126:127], v[162:163]
	v_pk_fma_f32 v[164:165], v[60:61], v[158:159], v[164:165]
	v_pk_fma_f32 v[166:167], v[92:93], v[126:127], v[166:167]
	v_pk_fma_f32 v[168:169], v[92:93], v[158:159], v[168:169]
	v_pk_fma_f32 v[162:163], v[62:63], v[128:129], v[162:163]
	v_pk_fma_f32 v[164:165], v[62:63], v[160:161], v[164:165]
	v_pk_fma_f32 v[166:167], v[94:95], v[128:129], v[166:167]
	v_pk_fma_f32 v[168:169], v[94:95], v[160:161], v[168:169]
	v_add_f32_e32 v162, v162, v163
	v_add_f32_e32 v166, v166, v167
	v_add_f32_e32 v164, v164, v165
	v_add_f32_e32 v168, v168, v169
	v_permlane32_swap_b32_e32 v162, v166
	v_add_f32_e64 v176, -v162, -v166
	v_permlane32_swap_b32_e32 v164, v168
	v_add_f32_e32 v177, v164, v168
	v_permlane32_swap_b32_e32 v176, v174
	v_cvt_pk_bf16_f32 v178, v177, v177
	s_nop 0
	v_mfma_f32_32x32x2_f32 v[32:47], v170, v176, v[32:47]
	ds_read_b128 v[130:133], v179 offset:8192
	ds_read_b128 v[134:137], v179 offset:8224
	ds_read_b128 v[138:141], v179 offset:8256
	ds_read_b128 v[142:145], v179 offset:8288
	ds_read_b128 v[146:149], v179 offset:8320
	ds_read_b128 v[150:153], v179 offset:8352
	ds_read_b128 v[154:157], v179 offset:8384
	ds_read_b128 v[158:161], v179 offset:8416
	v_mfma_f32_32x32x2_f32 v[48:63], v171, v176, v[48:63]
	v_add_u32_e32 v179, s39, v179
	v_add_u32_e32 v180, s39, v180
	v_add_u32_e32 v181, s39, v181
	ds_read_b128 v[98:101], v179 offset:2048
	ds_read_b128 v[102:105], v179 offset:2080
	ds_read_b128 v[106:109], v179 offset:2112
	ds_read_b128 v[110:113], v179 offset:2144
	ds_read_b128 v[114:117], v179 offset:2176
	ds_read_b128 v[118:121], v179 offset:2208
	ds_read_b128 v[122:125], v179 offset:2240
	ds_read_b128 v[126:129], v179 offset:2272
	v_mfma_f32_32x32x2_f32 v[64:79], v170, v174, v[64:79]
	ds_read_b32 v172, v180
	ds_read_b32 v173, v180 offset:128
	ds_read_b32 v175, v181
	v_mfma_f32_32x32x2_f32 v[80:95], v171, v174, v[80:95]
	global_store_short v182, v178, s[42:43]
	s_add_u32 s42, s42, s74
	s_addc_u32 s43, s43, s3
	s_nop 7
	s_nop 7
	s_nop 3
	s_waitcnt lgkmcnt(0)
	v_pk_mul_f32 v[162:163], v[32:33], v[98:99]
	v_pk_mul_f32 v[164:165], v[32:33], v[130:131]
	v_pk_mul_f32 v[166:167], v[64:65], v[98:99]
	v_pk_mul_f32 v[168:169], v[64:65], v[130:131]
	v_pk_fma_f32 v[162:163], v[34:35], v[100:101], v[162:163]
	v_pk_fma_f32 v[164:165], v[34:35], v[132:133], v[164:165]
	v_pk_fma_f32 v[166:167], v[66:67], v[100:101], v[166:167]
	v_pk_fma_f32 v[168:169], v[66:67], v[132:133], v[168:169]
	v_pk_fma_f32 v[162:163], v[36:37], v[102:103], v[162:163]
	v_pk_fma_f32 v[164:165], v[36:37], v[134:135], v[164:165]
	v_pk_fma_f32 v[166:167], v[68:69], v[102:103], v[166:167]
	v_pk_fma_f32 v[168:169], v[68:69], v[134:135], v[168:169]
	v_pk_fma_f32 v[162:163], v[38:39], v[104:105], v[162:163]
	v_pk_fma_f32 v[164:165], v[38:39], v[136:137], v[164:165]
	v_pk_fma_f32 v[166:167], v[70:71], v[104:105], v[166:167]
	v_pk_fma_f32 v[168:169], v[70:71], v[136:137], v[168:169]
	v_pk_fma_f32 v[162:163], v[40:41], v[106:107], v[162:163]
	v_pk_fma_f32 v[164:165], v[40:41], v[138:139], v[164:165]
	v_pk_fma_f32 v[166:167], v[72:73], v[106:107], v[166:167]
	v_pk_fma_f32 v[168:169], v[72:73], v[138:139], v[168:169]
	v_pk_fma_f32 v[162:163], v[42:43], v[108:109], v[162:163]
	v_pk_fma_f32 v[164:165], v[42:43], v[140:141], v[164:165]
	v_pk_fma_f32 v[166:167], v[74:75], v[108:109], v[166:167]
	v_pk_fma_f32 v[168:169], v[74:75], v[140:141], v[168:169]
	v_pk_fma_f32 v[162:163], v[44:45], v[110:111], v[162:163]
	v_pk_fma_f32 v[164:165], v[44:45], v[142:143], v[164:165]
	v_pk_fma_f32 v[166:167], v[76:77], v[110:111], v[166:167]
	v_pk_fma_f32 v[168:169], v[76:77], v[142:143], v[168:169]
	v_pk_fma_f32 v[162:163], v[46:47], v[112:113], v[162:163]
	v_pk_fma_f32 v[164:165], v[46:47], v[144:145], v[164:165]
	v_pk_fma_f32 v[166:167], v[78:79], v[112:113], v[166:167]
	v_pk_fma_f32 v[168:169], v[78:79], v[144:145], v[168:169]
	v_pk_fma_f32 v[162:163], v[48:49], v[114:115], v[162:163]
	v_pk_fma_f32 v[164:165], v[48:49], v[146:147], v[164:165]
	v_pk_fma_f32 v[166:167], v[80:81], v[114:115], v[166:167]
	v_pk_fma_f32 v[168:169], v[80:81], v[146:147], v[168:169]
	v_pk_fma_f32 v[162:163], v[50:51], v[116:117], v[162:163]
	v_pk_fma_f32 v[164:165], v[50:51], v[148:149], v[164:165]
	v_pk_fma_f32 v[166:167], v[82:83], v[116:117], v[166:167]
	v_pk_fma_f32 v[168:169], v[82:83], v[148:149], v[168:169]
	v_pk_fma_f32 v[162:163], v[52:53], v[118:119], v[162:163]
	v_pk_fma_f32 v[164:165], v[52:53], v[150:151], v[164:165]
	v_pk_fma_f32 v[166:167], v[84:85], v[118:119], v[166:167]
	v_pk_fma_f32 v[168:169], v[84:85], v[150:151], v[168:169]
	v_pk_fma_f32 v[162:163], v[54:55], v[120:121], v[162:163]
	v_pk_fma_f32 v[164:165], v[54:55], v[152:153], v[164:165]
	v_pk_fma_f32 v[166:167], v[86:87], v[120:121], v[166:167]
	v_pk_fma_f32 v[168:169], v[86:87], v[152:153], v[168:169]
	v_pk_fma_f32 v[162:163], v[56:57], v[122:123], v[162:163]
	v_pk_fma_f32 v[164:165], v[56:57], v[154:155], v[164:165]
	v_pk_fma_f32 v[166:167], v[88:89], v[122:123], v[166:167]
	v_pk_fma_f32 v[168:169], v[88:89], v[154:155], v[168:169]
	v_pk_fma_f32 v[162:163], v[58:59], v[124:125], v[162:163]
	v_pk_fma_f32 v[164:165], v[58:59], v[156:157], v[164:165]
	v_pk_fma_f32 v[166:167], v[90:91], v[124:125], v[166:167]
	v_pk_fma_f32 v[168:169], v[90:91], v[156:157], v[168:169]
	v_pk_fma_f32 v[162:163], v[60:61], v[126:127], v[162:163]
	v_pk_fma_f32 v[164:165], v[60:61], v[158:159], v[164:165]
	v_pk_fma_f32 v[166:167], v[92:93], v[126:127], v[166:167]
	v_pk_fma_f32 v[168:169], v[92:93], v[158:159], v[168:169]
	v_pk_fma_f32 v[162:163], v[62:63], v[128:129], v[162:163]
	v_pk_fma_f32 v[164:165], v[62:63], v[160:161], v[164:165]
	v_pk_fma_f32 v[166:167], v[94:95], v[128:129], v[166:167]
	v_pk_fma_f32 v[168:169], v[94:95], v[160:161], v[168:169]
	v_add_f32_e32 v162, v162, v163
	v_add_f32_e32 v166, v166, v167
	v_add_f32_e32 v164, v164, v165
	v_add_f32_e32 v168, v168, v169
	v_permlane32_swap_b32_e32 v162, v166
	v_add_f32_e64 v176, -v162, -v166
	v_permlane32_swap_b32_e32 v164, v168
	v_add_f32_e32 v177, v164, v168
	v_permlane32_swap_b32_e32 v176, v175
	v_cvt_pk_bf16_f32 v178, v177, v177
	s_nop 0
	v_mfma_f32_32x32x2_f32 v[32:47], v172, v176, v[32:47]
	ds_read_b128 v[130:133], v179 offset:8192
	ds_read_b128 v[134:137], v179 offset:8224
	ds_read_b128 v[138:141], v179 offset:8256
	ds_read_b128 v[142:145], v179 offset:8288
	ds_read_b128 v[146:149], v179 offset:8320
	ds_read_b128 v[150:153], v179 offset:8352
	ds_read_b128 v[154:157], v179 offset:8384
	ds_read_b128 v[158:161], v179 offset:8416
	v_mfma_f32_32x32x2_f32 v[48:63], v173, v176, v[48:63]
	ds_read_b128 v[98:101], v183 offset:0
	ds_read_b128 v[102:105], v183 offset:32
	ds_read_b128 v[106:109], v183 offset:64
	ds_read_b128 v[110:113], v183 offset:96
	ds_read_b128 v[114:117], v183 offset:128
	ds_read_b128 v[118:121], v183 offset:160
	ds_read_b128 v[122:125], v183 offset:192
	ds_read_b128 v[126:129], v183 offset:224
	v_mfma_f32_32x32x2_f32 v[64:79], v172, v175, v[64:79]
	v_mfma_f32_32x32x2_f32 v[80:95], v173, v175, v[80:95]
	global_store_short v182, v178, s[42:43]
	s_add_u32 s42, s42, s74
	s_addc_u32 s43, s43, s3
	s_nop 7
	s_nop 7
	s_nop 3
	s_waitcnt lgkmcnt(0)
	v_pk_mul_f32 v[164:165], v[32:33], v[130:131]
	v_pk_mul_f32 v[168:169], v[64:65], v[130:131]
	v_pk_fma_f32 v[164:165], v[34:35], v[132:133], v[164:165]
	v_pk_fma_f32 v[168:169], v[66:67], v[132:133], v[168:169]
	v_pk_fma_f32 v[164:165], v[36:37], v[134:135], v[164:165]
	v_pk_fma_f32 v[168:169], v[68:69], v[134:135], v[168:169]
	v_pk_fma_f32 v[164:165], v[38:39], v[136:137], v[164:165]
	v_pk_fma_f32 v[168:169], v[70:71], v[136:137], v[168:169]
	v_pk_fma_f32 v[164:165], v[40:41], v[138:139], v[164:165]
	v_pk_fma_f32 v[168:169], v[72:73], v[138:139], v[168:169]
	v_pk_fma_f32 v[164:165], v[42:43], v[140:141], v[164:165]
	v_pk_fma_f32 v[168:169], v[74:75], v[140:141], v[168:169]
	v_pk_fma_f32 v[164:165], v[44:45], v[142:143], v[164:165]
	v_pk_fma_f32 v[168:169], v[76:77], v[142:143], v[168:169]
	v_pk_fma_f32 v[164:165], v[46:47], v[144:145], v[164:165]
	v_pk_fma_f32 v[168:169], v[78:79], v[144:145], v[168:169]
	v_pk_fma_f32 v[164:165], v[48:49], v[146:147], v[164:165]
	v_pk_fma_f32 v[168:169], v[80:81], v[146:147], v[168:169]
	v_pk_fma_f32 v[164:165], v[50:51], v[148:149], v[164:165]
	v_pk_fma_f32 v[168:169], v[82:83], v[148:149], v[168:169]
	v_pk_fma_f32 v[164:165], v[52:53], v[150:151], v[164:165]
	v_pk_fma_f32 v[168:169], v[84:85], v[150:151], v[168:169]
	v_pk_fma_f32 v[164:165], v[54:55], v[152:153], v[164:165]
	v_pk_fma_f32 v[168:169], v[86:87], v[152:153], v[168:169]
	v_pk_fma_f32 v[164:165], v[56:57], v[154:155], v[164:165]
	v_pk_fma_f32 v[168:169], v[88:89], v[154:155], v[168:169]
	v_pk_fma_f32 v[164:165], v[58:59], v[156:157], v[164:165]
	v_pk_fma_f32 v[168:169], v[90:91], v[156:157], v[168:169]
	v_pk_fma_f32 v[164:165], v[60:61], v[158:159], v[164:165]
	v_pk_fma_f32 v[168:169], v[92:93], v[158:159], v[168:169]
	v_pk_fma_f32 v[164:165], v[62:63], v[160:161], v[164:165]
	v_pk_fma_f32 v[168:169], v[94:95], v[160:161], v[168:169]
	v_add_f32_e32 v164, v164, v165
	v_add_f32_e32 v168, v168, v169
	v_pk_mul_f32 v[32:33], v[32:33], v[98:99]
	v_pk_mul_f32 v[34:35], v[34:35], v[100:101]
	v_pk_mul_f32 v[36:37], v[36:37], v[102:103]
	v_pk_mul_f32 v[38:39], v[38:39], v[104:105]
	v_pk_mul_f32 v[40:41], v[40:41], v[106:107]
	v_pk_mul_f32 v[42:43], v[42:43], v[108:109]
	v_pk_mul_f32 v[44:45], v[44:45], v[110:111]
	v_pk_mul_f32 v[46:47], v[46:47], v[112:113]
	v_permlane32_swap_b32_e32 v164, v168
	v_add_f32_e32 v177, v164, v168
	v_cvt_pk_bf16_f32 v178, v177, v177
	global_store_short v182, v178, s[42:43]
	v_pk_mul_f32 v[48:49], v[48:49], v[114:115]
	v_pk_mul_f32 v[50:51], v[50:51], v[116:117]
	v_pk_mul_f32 v[52:53], v[52:53], v[118:119]
	v_pk_mul_f32 v[54:55], v[54:55], v[120:121]
	v_pk_mul_f32 v[56:57], v[56:57], v[122:123]
	v_pk_mul_f32 v[58:59], v[58:59], v[124:125]
	v_pk_mul_f32 v[60:61], v[60:61], v[126:127]
	v_pk_mul_f32 v[62:63], v[62:63], v[128:129]
	v_pk_mul_f32 v[64:65], v[64:65], v[98:99]
	v_pk_mul_f32 v[66:67], v[66:67], v[100:101]
	v_pk_mul_f32 v[68:69], v[68:69], v[102:103]
	v_pk_mul_f32 v[70:71], v[70:71], v[104:105]
	v_pk_mul_f32 v[72:73], v[72:73], v[106:107]
	v_pk_mul_f32 v[74:75], v[74:75], v[108:109]
	v_pk_mul_f32 v[76:77], v[76:77], v[110:111]
	v_pk_mul_f32 v[78:79], v[78:79], v[112:113]
	v_pk_mul_f32 v[80:81], v[80:81], v[114:115]
	v_pk_mul_f32 v[82:83], v[82:83], v[116:117]
	v_pk_mul_f32 v[84:85], v[84:85], v[118:119]
	v_pk_mul_f32 v[86:87], v[86:87], v[120:121]
	v_pk_mul_f32 v[88:89], v[88:89], v[122:123]
	v_pk_mul_f32 v[90:91], v[90:91], v[124:125]
	v_pk_mul_f32 v[92:93], v[92:93], v[126:127]
	v_pk_mul_f32 v[94:95], v[94:95], v[128:129]
